# RWKV and HGRN scan loops: back-edge block rotated into the loop tail (one taken branch per iteration instead of two)
# baseline (speedup 1.0000x reference)
; #define HG_LD(X, tl_) do { const float* f_ = sF + (tl_) * 128 + seg * 4; const float* q_ = sQ + (tl_) * 128 + seg * 4;   \
;                 X##f0 = *(const f32x4*)(f_); X##f1 = *(const f32x4*)(f_ + 64); X##q0 = *(const f32x4*)(q_); X##q1 = *(const f32x4*)(q_ + 64); \
;                 X##va = sDV[(tl_) * 64 + cp]; X##vb = sDV[(tl_) * 64 + 32 + cp]; } while (0)
; __device__ __forceinline__ void phase_hgrn(KP P, int l_, unsigned char* shm) {
;     ...
;             {
;                 f32x4 Af0, Af1, Aq0, Aq1; float Ava, Avb;
;                 f32x4 Bf0, Bf1, Bq0, Bq1; float Bva, Bvb;
;                 HG_LD(A, 0);
; #pragma unroll 2
;                 for (int tl = 0; tl < T; tl += 2) {
;                     HG_LD(B, tl + 1);
;                     HG_STEP(A, tl);
;                     HG_LD(A, tl + 2);
;                     HG_STEP(B, tl + 1);
;                 }
.LBB0_2164:
	ds_read_b128 v[34:37], v129
	ds_read_b128 v[30:33], v129 offset:256
	ds_read_b128 v[26:29], v129 offset:16384
	ds_read_b128 v[22:25], v129 offset:16640
	ds_read2_b32 v[80:81], v130 offset1:32
	s_waitcnt lgkmcnt(8)
	v_pk_fma_f32 v[70:71], v[20:21], v[70:71], v[78:79] op_sel_hi:[1,1,0]
	v_pk_fma_f32 v[76:77], v[20:21], v[76:77], v[78:79] op_sel:[0,0,1]
	v_pk_fma_f32 v[64:65], v[18:19], v[64:65], v[78:79] op_sel_hi:[1,1,0]
	v_pk_fma_f32 v[82:83], v[18:19], v[62:63], v[78:79] op_sel:[0,0,1]
	s_waitcnt lgkmcnt(7)
	v_pk_fma_f32 v[68:69], v[14:15], v[68:69], v[78:79] op_sel_hi:[1,1,0]
	v_pk_fma_f32 v[74:75], v[14:15], v[74:75], v[78:79] op_sel:[0,0,1]
	v_pk_fma_f32 v[66:67], v[16:17], v[66:67], v[78:79] op_sel_hi:[1,1,0]
	v_pk_fma_f32 v[72:73], v[16:17], v[72:73], v[78:79] op_sel:[0,0,1]
	v_pk_mul_f32 v[14:15], v[12:13], v[70:71]
	v_pk_mul_f32 v[12:13], v[12:13], v[76:77]
	v_pk_fma_f32 v[14:15], v[10:11], v[64:65], v[14:15]
	v_pk_fma_f32 v[10:11], v[10:11], v[82:83], v[12:13]
	v_pk_fma_f32 v[12:13], v[8:9], v[66:67], v[14:15]
	v_pk_fma_f32 v[8:9], v[8:9], v[72:73], v[10:11]
	v_pk_fma_f32 v[12:13], v[6:7], v[68:69], v[12:13]
	v_pk_fma_f32 v[6:7], v[6:7], v[74:75], v[8:9]
	v_add_f32_e32 v137, v12, v13
	v_add_f32_e32 v141, v6, v7
	s_waitcnt lgkmcnt(0)
	ds_read_b128 v[18:21], v129 offset:512
	ds_read_b128 v[14:17], v129 offset:768
	ds_read_b128 v[10:13], v129 offset:16896
	ds_read_b128 v[6:9], v129 offset:17152
	ds_read2_b32 v[62:63], v130 offset0:64 offset1:96
	v_pk_fma_f32 v[70:71], v[70:71], v[36:37], v[80:81] op_sel_hi:[1,1,0]
	v_pk_fma_f32 v[76:77], v[36:37], v[76:77], v[80:81] op_sel:[0,0,1]
	v_pk_fma_f32 v[64:65], v[64:65], v[34:35], v[80:81] op_sel_hi:[1,1,0]
	v_pk_fma_f32 v[78:79], v[34:35], v[82:83], v[80:81] op_sel:[0,0,1]
	v_pk_fma_f32 v[82:83], v[68:69], v[30:31], v[80:81] op_sel_hi:[1,1,0]
	v_pk_fma_f32 v[84:85], v[74:75], v[30:31], v[80:81] op_sel:[0,0,1]
	v_pk_fma_f32 v[86:87], v[66:67], v[32:33], v[80:81] op_sel_hi:[1,1,0]
	v_pk_fma_f32 v[88:89], v[72:73], v[32:33], v[80:81] op_sel:[0,0,1]
	v_pk_mul_f32 v[30:31], v[28:29], v[70:71]
	v_pk_mul_f32 v[28:29], v[28:29], v[76:77]
	v_pk_fma_f32 v[30:31], v[26:27], v[64:65], v[30:31]
	v_pk_fma_f32 v[26:27], v[26:27], v[78:79], v[28:29]
	v_pk_fma_f32 v[28:29], v[24:25], v[86:87], v[30:31]
	v_pk_fma_f32 v[24:25], v[24:25], v[88:89], v[26:27]
	v_pk_fma_f32 v[28:29], v[22:23], v[82:83], v[28:29]
	v_pk_fma_f32 v[22:23], v[22:23], v[84:85], v[24:25]
	v_add_f32_e32 v138, v28, v29
	v_add_f32_e32 v142, v22, v23
	s_waitcnt lgkmcnt(0)
	ds_read_b128 v[34:37], v129 offset:1024
	ds_read_b128 v[30:33], v129 offset:1280
	ds_read_b128 v[26:29], v129 offset:17408
	ds_read_b128 v[22:25], v129 offset:17664
	ds_read2_b32 v[66:67], v130 offset0:128 offset1:160
	v_pk_fma_f32 v[70:71], v[20:21], v[70:71], v[62:63] op_sel_hi:[1,1,0]
	v_pk_fma_f32 v[72:73], v[20:21], v[76:77], v[62:63] op_sel:[0,0,1]
	v_pk_fma_f32 v[64:65], v[18:19], v[64:65], v[62:63] op_sel_hi:[1,1,0]
	v_pk_fma_f32 v[68:69], v[18:19], v[78:79], v[62:63] op_sel:[0,0,1]
	v_pk_fma_f32 v[74:75], v[14:15], v[82:83], v[62:63] op_sel_hi:[1,1,0]
	v_pk_fma_f32 v[80:81], v[14:15], v[84:85], v[62:63] op_sel:[0,0,1]
	v_pk_fma_f32 v[82:83], v[16:17], v[86:87], v[62:63] op_sel_hi:[1,1,0]
	v_pk_fma_f32 v[84:85], v[16:17], v[88:89], v[62:63] op_sel:[0,0,1]
	v_pk_mul_f32 v[14:15], v[12:13], v[70:71]
	v_pk_mul_f32 v[12:13], v[12:13], v[72:73]
	v_pk_fma_f32 v[14:15], v[10:11], v[64:65], v[14:15]
	v_pk_fma_f32 v[10:11], v[10:11], v[68:69], v[12:13]
	v_pk_fma_f32 v[12:13], v[8:9], v[82:83], v[14:15]
	v_pk_fma_f32 v[8:9], v[8:9], v[84:85], v[10:11]
	v_pk_fma_f32 v[12:13], v[6:7], v[74:75], v[12:13]
	v_pk_fma_f32 v[6:7], v[6:7], v[80:81], v[8:9]
	v_add_f32_e32 v139, v12, v13
	v_add_f32_e32 v143, v6, v7
	s_waitcnt lgkmcnt(0)
	v_pk_fma_f32 v[70:71], v[70:71], v[36:37], v[66:67] op_sel_hi:[1,1,0]
	v_pk_fma_f32 v[76:77], v[36:37], v[72:73], v[66:67] op_sel:[0,0,1]
	v_pk_fma_f32 v[64:65], v[64:65], v[34:35], v[66:67] op_sel_hi:[1,1,0]
	v_pk_fma_f32 v[62:63], v[34:35], v[68:69], v[66:67] op_sel:[0,0,1]
	v_pk_fma_f32 v[68:69], v[74:75], v[30:31], v[66:67] op_sel_hi:[1,1,0]
	v_pk_fma_f32 v[74:75], v[80:81], v[30:31], v[66:67] op_sel:[0,0,1]
	v_pk_fma_f32 v[72:73], v[84:85], v[32:33], v[66:67] op_sel:[0,0,1]
	v_pk_fma_f32 v[66:67], v[82:83], v[32:33], v[66:67] op_sel_hi:[1,1,0]
	v_pk_mul_f32 v[30:31], v[28:29], v[70:71]
	v_pk_mul_f32 v[28:29], v[28:29], v[76:77]
	v_pk_fma_f32 v[30:31], v[26:27], v[64:65], v[30:31]
	v_pk_fma_f32 v[26:27], v[26:27], v[62:63], v[28:29]
	v_pk_fma_f32 v[28:29], v[24:25], v[66:67], v[30:31]
	v_pk_fma_f32 v[24:25], v[24:25], v[72:73], v[26:27]
	v_pk_fma_f32 v[28:29], v[22:23], v[68:69], v[28:29]
	v_pk_fma_f32 v[22:23], v[22:23], v[74:75], v[24:25]
	v_add_f32_e32 v140, v28, v29
	v_add_f32_e32 v144, v22, v23
	ds_read2_b32 v[78:79], v130 offset0:192 offset1:224
	ds_read_b128 v[18:21], v129 offset:1536
	ds_read_b128 v[14:17], v129 offset:1792
	ds_read_b128 v[10:13], v129 offset:17920
	ds_read_b128 v[6:9], v129 offset:18176
	v_cndmask_b32_e64 v145, v137, v138, s[60:61]
	v_cndmask_b32_e64 v146, v138, v137, s[60:61]
	v_cndmask_b32_e64 v147, v139, v140, s[60:61]
	v_cndmask_b32_e64 v148, v140, v139, s[60:61]
	v_cndmask_b32_e64 v149, v141, v142, s[60:61]
	v_cndmask_b32_e64 v150, v142, v141, s[60:61]
	v_cndmask_b32_e64 v151, v143, v144, s[60:61]
	v_cndmask_b32_e64 v152, v144, v143, s[60:61]
	v_add_f32_dpp v145, v146, v145 quad_perm:[1,0,3,2] row_mask:0xf bank_mask:0xf bound_ctrl:1
	v_add_f32_dpp v147, v148, v147 quad_perm:[1,0,3,2] row_mask:0xf bank_mask:0xf bound_ctrl:1
	v_add_f32_dpp v149, v150, v149 quad_perm:[1,0,3,2] row_mask:0xf bank_mask:0xf bound_ctrl:1
	v_add_f32_dpp v151, v152, v151 quad_perm:[1,0,3,2] row_mask:0xf bank_mask:0xf bound_ctrl:1
	v_cndmask_b32_e64 v146, v147, v145, s[62:63]
	v_cndmask_b32_e64 v148, v151, v149, s[62:63]
	v_cndmask_b32_e64 v133, v145, v147, s[62:63]
	v_cndmask_b32_e64 v134, v149, v151, s[62:63]
	v_add_f32_dpp v133, v146, v133 quad_perm:[2,3,0,1] row_mask:0xf bank_mask:0xf bound_ctrl:1
	v_add_f32_dpp v134, v148, v134 quad_perm:[2,3,0,1] row_mask:0xf bank_mask:0xf bound_ctrl:1
	ds_write_b32 v135, v133
	ds_write_b32 v136, v134
	s_add_i32 s17, s17, 4
	v_add_u32_e32 v135, 0x1000, v135
	v_add_u32_e32 v136, 0x1000, v136
	v_add_u32_e32 v130, 0x400, v130
	s_cmp_gt_u32 s17, 29
	v_add_u32_e32 v129, 0x800, v129
	s_cbranch_scc0 .LBB0_2164

; __device__ __forceinline__ void phase_rwkv(KP P, int l_, unsigned char* shm) {
;     ...
;                 f32x4 Aw0, Aw1, Akk0, Akk1, Ab0, Ab1, Ak0, Ak1, Ar0, Ar1; float Ava, Avb;
;                 f32x4 Bw0, Bw1, Bkk0, Bkk1, Bb0, Bb1, Bk0, Bk1, Br0, Br1; float Bva, Bvb;
;                 RW_LD(A, 0);
; #pragma unroll 2
;                 for (int tl = 0; tl < T; tl += 2) {
;                     RW_LD(B, tl + 1);
;                     RW_STEP(A, tl);
;                     RW_LD(A, tl + 2);
;                     RW_STEP(B, tl + 1);
;                 }
.LBB0_2517:
	v_pk_mul_f32 v[110:111], v[40:41], v[92:93]
	v_pk_mul_f32 v[40:41], v[40:41], v[100:101]
	v_pk_fma_f32 v[110:111], v[38:39], v[90:91], v[110:111]
	v_pk_fma_f32 v[38:39], v[38:39], v[98:99], v[40:41]
	v_pk_fma_f32 v[40:41], v[36:37], v[96:97], v[110:111]
	v_pk_fma_f32 v[36:37], v[36:37], v[104:105], v[38:39]
	v_pk_fma_f32 v[40:41], v[34:35], v[94:95], v[40:41]
	v_pk_fma_f32 v[34:35], v[34:35], v[102:103], v[36:37]
	v_add_f32_e32 v36, v40, v41
	v_add_f32_e32 v34, v34, v35
	ds_read_b128 v[62:65], v235
	v_add_f32_dpp v35, v36, v36 quad_perm:[1,0,3,2] row_mask:0xf bank_mask:0xf bound_ctrl:1
	v_add_f32_dpp v34, v34, v34 quad_perm:[1,0,3,2] row_mask:0xf bank_mask:0xf bound_ctrl:1
	ds_read_b128 v[50:53], v235 offset:16
	ds_read_b128 v[78:81], v235 offset:8192
	ds_read_b128 v[74:77], v235 offset:8208
	ds_read_b128 v[66:69], v235 offset:16384
	ds_read_b128 v[54:57], v235 offset:16400
	ds_read_b128 v[70:73], v235 offset:24576
	ds_read_b128 v[58:61], v235 offset:24592
	ds_read_b128 v[46:49], v235 offset:32768
	ds_read_b128 v[42:45], v235 offset:32784
	v_add_f32_dpp v35, v35, v35 quad_perm:[2,3,0,1] row_mask:0xf bank_mask:0xf bound_ctrl:1
	v_add_f32_dpp v36, v34, v34 quad_perm:[2,3,0,1] row_mask:0xf bank_mask:0xf bound_ctrl:1
	v_add_u32_e32 v186, s43, v252
	v_add_f32_dpp v34, v35, v35 row_half_mirror row_mask:0xf bank_mask:0xf bound_ctrl:1
	v_add_f32_dpp v36, v36, v36 row_half_mirror row_mask:0xf bank_mask:0xf bound_ctrl:1
	v_pk_mul_f32 v[38:39], v[26:27], v[34:35] op_sel_hi:[1,0] neg_lo:[0,1] neg_hi:[0,1]
	v_pk_mul_f32 v[26:27], v[26:27], v[36:37] op_sel_hi:[1,0] neg_lo:[0,1] neg_hi:[0,1]
	v_pk_fma_f32 v[38:39], v[10:11], v[90:91], v[38:39]
	v_pk_fma_f32 v[10:11], v[10:11], v[98:99], v[26:27]
	s_waitcnt lgkmcnt(13)
	v_pk_fma_f32 v[110:111], v[30:31], v[106:107], v[38:39] op_sel_hi:[1,0,1]
	v_pk_fma_f32 v[98:99], v[30:31], v[106:107], v[10:11] op_sel:[0,1,0]
	v_pk_mul_f32 v[10:11], v[28:29], v[34:35] op_sel_hi:[1,0] neg_lo:[0,1] neg_hi:[0,1]
	v_pk_mul_f32 v[170:171], v[28:29], v[36:37] op_sel_hi:[1,0] neg_lo:[0,1] neg_hi:[0,1]
	ds_read2_b32 v[108:109], v186 offset1:32
	v_pk_fma_f32 v[10:11], v[12:13], v[92:93], v[10:11]
	v_pk_fma_f32 v[170:171], v[12:13], v[100:101], v[170:171]
	v_pk_fma_f32 v[92:93], v[32:33], v[106:107], v[10:11] op_sel_hi:[1,0,1]
	v_pk_fma_f32 v[100:101], v[32:33], v[106:107], v[170:171] op_sel:[0,1,0]
	v_pk_mul_f32 v[10:11], v[6:7], v[34:35] op_sel_hi:[1,0] neg_lo:[0,1] neg_hi:[0,1]
	v_pk_mul_f32 v[6:7], v[6:7], v[36:37] op_sel_hi:[1,0] neg_lo:[0,1] neg_hi:[0,1]
	v_pk_fma_f32 v[10:11], v[0:1], v[94:95], v[10:11]
	v_pk_fma_f32 v[0:1], v[0:1], v[102:103], v[6:7]
	s_waitcnt lgkmcnt(13)
	v_pk_fma_f32 v[94:95], v[22:23], v[106:107], v[10:11] op_sel_hi:[1,0,1]
	v_pk_fma_f32 v[102:103], v[22:23], v[106:107], v[0:1] op_sel:[0,1,0]
	v_pk_mul_f32 v[0:1], v[8:9], v[34:35] op_sel_hi:[1,0] neg_lo:[0,1] neg_hi:[0,1]
	v_pk_mul_f32 v[170:171], v[8:9], v[36:37] op_sel_hi:[1,0] neg_lo:[0,1] neg_hi:[0,1]
	v_pk_fma_f32 v[0:1], v[2:3], v[96:97], v[0:1]
	v_pk_fma_f32 v[170:171], v[2:3], v[104:105], v[170:171]
	v_pk_fma_f32 v[96:97], v[24:25], v[106:107], v[0:1] op_sel_hi:[1,0,1]
	v_pk_fma_f32 v[104:105], v[24:25], v[106:107], v[170:171] op_sel:[0,1,0]
	s_waitcnt lgkmcnt(11)
	v_pk_mul_f32 v[2:3], v[20:21], v[100:101]
	v_pk_mul_f32 v[0:1], v[20:21], v[92:93]
	v_pk_fma_f32 v[2:3], v[18:19], v[98:99], v[2:3]
	v_pk_fma_f32 v[0:1], v[18:19], v[110:111], v[0:1]
	v_pk_fma_f32 v[8:9], v[16:17], v[104:105], v[2:3]
	v_pk_fma_f32 v[6:7], v[16:17], v[96:97], v[0:1]
	v_pk_fma_f32 v[8:9], v[14:15], v[102:103], v[8:9]
	v_pk_fma_f32 v[6:7], v[14:15], v[94:95], v[6:7]
	v_add_f32_e32 v158, v8, v9
	v_add_f32_e32 v157, v6, v7
	s_waitcnt lgkmcnt(6)
	v_pk_mul_f32 v[106:107], v[80:81], v[92:93]
	v_pk_mul_f32 v[80:81], v[80:81], v[100:101]
	v_pk_fma_f32 v[106:107], v[78:79], v[110:111], v[106:107]
	v_pk_fma_f32 v[78:79], v[78:79], v[98:99], v[80:81]
	s_waitcnt lgkmcnt(5)
	v_pk_fma_f32 v[80:81], v[76:77], v[96:97], v[106:107]
	v_pk_fma_f32 v[76:77], v[76:77], v[104:105], v[78:79]
	v_pk_fma_f32 v[80:81], v[74:75], v[94:95], v[80:81]
	v_pk_fma_f32 v[74:75], v[74:75], v[102:103], v[76:77]
	v_add_f32_e32 v4, v80, v81
	v_add_f32_e32 v74, v74, v75
	s_waitcnt lgkmcnt(0)
	v_add_f32_dpp v4, v4, v4 quad_perm:[1,0,3,2] row_mask:0xf bank_mask:0xf bound_ctrl:1
	v_add_f32_dpp v74, v74, v74 quad_perm:[1,0,3,2] row_mask:0xf bank_mask:0xf bound_ctrl:1
	ds_read_b128 v[22:25], v235 offset:256
	ds_read_b128 v[10:13], v235 offset:272
	ds_read_b128 v[38:41], v235 offset:8448
	ds_read_b128 v[34:37], v235 offset:8464
	ds_read_b128 v[26:29], v235 offset:16640
	ds_read_b128 v[14:17], v235 offset:16656
	ds_read_b128 v[30:33], v235 offset:24832
	ds_read_b128 v[18:21], v235 offset:24848
	ds_read_b128 v[6:9], v235 offset:33024
	ds_read_b128 v[0:3], v235 offset:33040
	ds_read2_b32 v[90:91], v186 offset0:64 offset1:96
	v_add_f32_dpp v4, v4, v4 quad_perm:[2,3,0,1] row_mask:0xf bank_mask:0xf bound_ctrl:1
	v_add_f32_dpp v74, v74, v74 quad_perm:[2,3,0,1] row_mask:0xf bank_mask:0xf bound_ctrl:1
	s_nop 0
	v_add_f32_dpp v4, v4, v4 row_half_mirror row_mask:0xf bank_mask:0xf bound_ctrl:1
	v_add_f32_dpp v74, v74, v74 row_half_mirror row_mask:0xf bank_mask:0xf bound_ctrl:1
	v_pk_mul_f32 v[78:79], v[66:67], v[4:5] op_sel_hi:[1,0] neg_lo:[0,1] neg_hi:[0,1]
	v_pk_mul_f32 v[66:67], v[66:67], v[74:75] op_sel_hi:[1,0] neg_lo:[0,1] neg_hi:[0,1]
	v_pk_fma_f32 v[78:79], v[62:63], v[110:111], v[78:79]
	v_pk_fma_f32 v[62:63], v[62:63], v[98:99], v[66:67]
	v_pk_fma_f32 v[106:107], v[70:71], v[108:109], v[78:79] op_sel_hi:[1,0,1]
	v_pk_fma_f32 v[98:99], v[70:71], v[108:109], v[62:63] op_sel:[0,1,0]
	v_pk_mul_f32 v[62:63], v[68:69], v[4:5] op_sel_hi:[1,0] neg_lo:[0,1] neg_hi:[0,1]
	v_pk_mul_f32 v[170:171], v[68:69], v[74:75] op_sel_hi:[1,0] neg_lo:[0,1] neg_hi:[0,1]
	v_pk_fma_f32 v[62:63], v[64:65], v[92:93], v[62:63]
	v_pk_fma_f32 v[170:171], v[64:65], v[100:101], v[170:171]
	v_pk_fma_f32 v[110:111], v[72:73], v[108:109], v[62:63] op_sel_hi:[1,0,1]
	v_pk_fma_f32 v[112:113], v[72:73], v[108:109], v[170:171] op_sel:[0,1,0]
	v_pk_mul_f32 v[62:63], v[54:55], v[4:5] op_sel_hi:[1,0] neg_lo:[0,1] neg_hi:[0,1]
	v_pk_mul_f32 v[54:55], v[54:55], v[74:75] op_sel_hi:[1,0] neg_lo:[0,1] neg_hi:[0,1]
	v_pk_fma_f32 v[62:63], v[50:51], v[94:95], v[62:63]
	v_pk_fma_f32 v[50:51], v[50:51], v[102:103], v[54:55]
	v_pk_fma_f32 v[114:115], v[58:59], v[108:109], v[62:63] op_sel_hi:[1,0,1]
	v_pk_fma_f32 v[116:117], v[58:59], v[108:109], v[50:51] op_sel:[0,1,0]
	v_pk_mul_f32 v[50:51], v[56:57], v[4:5] op_sel_hi:[1,0] neg_lo:[0,1] neg_hi:[0,1]
	v_pk_mul_f32 v[170:171], v[56:57], v[74:75] op_sel_hi:[1,0] neg_lo:[0,1] neg_hi:[0,1]
	v_pk_fma_f32 v[50:51], v[52:53], v[96:97], v[50:51]
	v_pk_fma_f32 v[170:171], v[52:53], v[104:105], v[170:171]
	v_pk_fma_f32 v[118:119], v[60:61], v[108:109], v[50:51] op_sel_hi:[1,0,1]
	v_pk_fma_f32 v[120:121], v[60:61], v[108:109], v[170:171] op_sel:[0,1,0]
	v_pk_mul_f32 v[50:51], v[48:49], v[110:111]
	v_pk_mul_f32 v[48:49], v[48:49], v[112:113]
	v_pk_fma_f32 v[50:51], v[46:47], v[106:107], v[50:51]
	v_pk_fma_f32 v[46:47], v[46:47], v[98:99], v[48:49]
	v_pk_fma_f32 v[48:49], v[44:45], v[118:119], v[50:51]
	v_pk_fma_f32 v[44:45], v[44:45], v[120:121], v[46:47]
	v_pk_fma_f32 v[48:49], v[42:43], v[114:115], v[48:49]
	v_pk_fma_f32 v[42:43], v[42:43], v[116:117], v[44:45]
	v_add_f32_e32 v159, v48, v49
	v_add_f32_e32 v160, v42, v43
	s_waitcnt lgkmcnt(6)
	v_pk_mul_f32 v[92:93], v[40:41], v[110:111]
	v_pk_mul_f32 v[40:41], v[40:41], v[112:113]
	v_pk_fma_f32 v[92:93], v[38:39], v[106:107], v[92:93]
	v_pk_fma_f32 v[38:39], v[38:39], v[98:99], v[40:41]
	s_waitcnt lgkmcnt(5)
	v_pk_fma_f32 v[40:41], v[36:37], v[118:119], v[92:93]
	v_pk_fma_f32 v[36:37], v[36:37], v[120:121], v[38:39]
	v_pk_fma_f32 v[40:41], v[34:35], v[114:115], v[40:41]
	v_pk_fma_f32 v[34:35], v[34:35], v[116:117], v[36:37]
	v_add_f32_e32 v4, v40, v41
	v_add_f32_e32 v34, v34, v35
	s_waitcnt lgkmcnt(0)
	v_add_f32_dpp v4, v4, v4 quad_perm:[1,0,3,2] row_mask:0xf bank_mask:0xf bound_ctrl:1
	v_add_f32_dpp v34, v34, v34 quad_perm:[1,0,3,2] row_mask:0xf bank_mask:0xf bound_ctrl:1
	ds_read_b128 v[62:65], v235 offset:512
	ds_read_b128 v[50:53], v235 offset:528
	ds_read_b128 v[78:81], v235 offset:8704
	ds_read_b128 v[74:77], v235 offset:8720
	ds_read_b128 v[66:69], v235 offset:16896
	ds_read_b128 v[54:57], v235 offset:16912
	ds_read_b128 v[70:73], v235 offset:25088
	ds_read_b128 v[58:61], v235 offset:25104
	ds_read_b128 v[46:49], v235 offset:33280
	ds_read_b128 v[42:45], v235 offset:33296
	ds_read2_b32 v[96:97], v186 offset0:128 offset1:160
	v_add_f32_dpp v4, v4, v4 quad_perm:[2,3,0,1] row_mask:0xf bank_mask:0xf bound_ctrl:1
	v_add_f32_dpp v34, v34, v34 quad_perm:[2,3,0,1] row_mask:0xf bank_mask:0xf bound_ctrl:1
	s_nop 0
	v_add_f32_dpp v4, v4, v4 row_half_mirror row_mask:0xf bank_mask:0xf bound_ctrl:1
	v_add_f32_dpp v34, v34, v34 row_half_mirror row_mask:0xf bank_mask:0xf bound_ctrl:1
	v_pk_mul_f32 v[38:39], v[26:27], v[4:5] op_sel_hi:[1,0] neg_lo:[0,1] neg_hi:[0,1]
	v_pk_mul_f32 v[26:27], v[26:27], v[34:35] op_sel_hi:[1,0] neg_lo:[0,1] neg_hi:[0,1]
	v_pk_fma_f32 v[38:39], v[22:23], v[106:107], v[38:39]
	v_pk_fma_f32 v[22:23], v[22:23], v[98:99], v[26:27]
	v_pk_fma_f32 v[92:93], v[30:31], v[90:91], v[38:39] op_sel_hi:[1,0,1]
	v_pk_fma_f32 v[94:95], v[30:31], v[90:91], v[22:23] op_sel:[0,1,0]
	v_pk_mul_f32 v[22:23], v[28:29], v[4:5] op_sel_hi:[1,0] neg_lo:[0,1] neg_hi:[0,1]
	v_pk_mul_f32 v[170:171], v[28:29], v[34:35] op_sel_hi:[1,0] neg_lo:[0,1] neg_hi:[0,1]
	v_pk_fma_f32 v[22:23], v[24:25], v[110:111], v[22:23]
	v_pk_fma_f32 v[170:171], v[24:25], v[112:113], v[170:171]
	v_pk_fma_f32 v[100:101], v[32:33], v[90:91], v[22:23] op_sel_hi:[1,0,1]
	v_pk_fma_f32 v[102:103], v[32:33], v[90:91], v[170:171] op_sel:[0,1,0]
	v_pk_mul_f32 v[22:23], v[14:15], v[4:5] op_sel_hi:[1,0] neg_lo:[0,1] neg_hi:[0,1]
	v_pk_mul_f32 v[14:15], v[14:15], v[34:35] op_sel_hi:[1,0] neg_lo:[0,1] neg_hi:[0,1]
	v_pk_fma_f32 v[22:23], v[10:11], v[114:115], v[22:23]
	v_pk_fma_f32 v[10:11], v[10:11], v[116:117], v[14:15]
	v_pk_fma_f32 v[104:105], v[18:19], v[90:91], v[22:23] op_sel_hi:[1,0,1]
	v_pk_fma_f32 v[108:109], v[18:19], v[90:91], v[10:11] op_sel:[0,1,0]
	v_pk_mul_f32 v[10:11], v[16:17], v[4:5] op_sel_hi:[1,0] neg_lo:[0,1] neg_hi:[0,1]
	v_pk_mul_f32 v[170:171], v[16:17], v[34:35] op_sel_hi:[1,0] neg_lo:[0,1] neg_hi:[0,1]
	v_pk_fma_f32 v[10:11], v[12:13], v[118:119], v[10:11]
	v_pk_fma_f32 v[170:171], v[12:13], v[120:121], v[170:171]
	v_pk_fma_f32 v[110:111], v[20:21], v[90:91], v[10:11] op_sel_hi:[1,0,1]
	v_pk_fma_f32 v[112:113], v[20:21], v[90:91], v[170:171] op_sel:[0,1,0]
	v_pk_mul_f32 v[10:11], v[8:9], v[100:101]
	v_pk_mul_f32 v[8:9], v[8:9], v[102:103]
	v_pk_fma_f32 v[10:11], v[6:7], v[92:93], v[10:11]
	v_pk_fma_f32 v[6:7], v[6:7], v[94:95], v[8:9]
	v_pk_fma_f32 v[8:9], v[2:3], v[110:111], v[10:11]
	v_pk_fma_f32 v[2:3], v[2:3], v[112:113], v[6:7]
	v_pk_fma_f32 v[8:9], v[0:1], v[104:105], v[8:9]
	v_pk_fma_f32 v[0:1], v[0:1], v[108:109], v[2:3]
	v_add_f32_e32 v161, v8, v9
	v_add_f32_e32 v162, v0, v1
	s_waitcnt lgkmcnt(6)
; __device__ __forceinline__ void phase_rwkv(KP P, int l_, unsigned char* shm) {
;     ...
;                 f32x4 Aw0, Aw1, Akk0, Akk1, Ab0, Ab1, Ak0, Ak1, Ar0, Ar1; float Ava, Avb;
;                 f32x4 Bw0, Bw1, Bkk0, Bkk1, Bb0, Bb1, Bk0, Bk1, Br0, Br1; float Bva, Bvb;
;                 RW_LD(A, 0);
; #pragma unroll 2
;                 for (int tl = 0; tl < T; tl += 2) {
;                     RW_LD(B, tl + 1);
;                     RW_STEP(A, tl);
;                     RW_LD(A, tl + 2);
;                     RW_STEP(B, tl + 1);
;                 }
	v_pk_mul_f32 v[90:91], v[80:81], v[100:101]
	v_pk_mul_f32 v[80:81], v[80:81], v[102:103]
	v_pk_fma_f32 v[90:91], v[78:79], v[92:93], v[90:91]
	v_pk_fma_f32 v[78:79], v[78:79], v[94:95], v[80:81]
	s_waitcnt lgkmcnt(5)
	v_pk_fma_f32 v[80:81], v[76:77], v[110:111], v[90:91]
	v_pk_fma_f32 v[76:77], v[76:77], v[112:113], v[78:79]
	v_pk_fma_f32 v[80:81], v[74:75], v[104:105], v[80:81]
	v_pk_fma_f32 v[74:75], v[74:75], v[108:109], v[76:77]
	v_add_f32_e32 v76, v80, v81
	v_add_f32_e32 v74, v74, v75
	s_waitcnt lgkmcnt(0)
	v_mov_b32_e32 v78, v97
	v_add_f32_dpp v75, v76, v76 quad_perm:[1,0,3,2] row_mask:0xf bank_mask:0xf bound_ctrl:1
	v_add_f32_dpp v74, v74, v74 quad_perm:[1,0,3,2] row_mask:0xf bank_mask:0xf bound_ctrl:1
	ds_read_b128 v[10:13], v235 offset:768
	ds_read_b128 v[0:3], v235 offset:784
	ds_read_b128 v[38:41], v235 offset:8960
	ds_read_b128 v[34:37], v235 offset:8976
	ds_read_b128 v[26:29], v235 offset:17152
	ds_read_b128 v[6:9], v235 offset:17168
	ds_read2_b32 v[106:107], v186 offset0:192 offset1:224
	ds_read_b128 v[30:33], v235 offset:25344
	ds_read_b128 v[22:25], v235 offset:25360
	ds_read_b128 v[18:21], v235 offset:33536
	ds_read_b128 v[14:17], v235 offset:33552
	v_add_f32_dpp v75, v75, v75 quad_perm:[2,3,0,1] row_mask:0xf bank_mask:0xf bound_ctrl:1
	v_add_f32_dpp v76, v74, v74 quad_perm:[2,3,0,1] row_mask:0xf bank_mask:0xf bound_ctrl:1
	s_waitcnt lgkmcnt(4)
	v_add_f32_dpp v74, v75, v75 row_half_mirror row_mask:0xf bank_mask:0xf bound_ctrl:1
	v_add_f32_dpp v76, v76, v76 row_half_mirror row_mask:0xf bank_mask:0xf bound_ctrl:1
	v_pk_mul_f32 v[80:81], v[66:67], v[74:75] op_sel_hi:[1,0] neg_lo:[0,1] neg_hi:[0,1]
	v_pk_mul_f32 v[66:67], v[66:67], v[76:77] op_sel_hi:[1,0] neg_lo:[0,1] neg_hi:[0,1]
	v_pk_fma_f32 v[80:81], v[62:63], v[92:93], v[80:81]
	v_pk_fma_f32 v[62:63], v[62:63], v[94:95], v[66:67]
	v_pk_fma_f32 v[90:91], v[70:71], v[96:97], v[80:81] op_sel_hi:[1,0,1]
	v_pk_fma_f32 v[98:99], v[70:71], v[78:79], v[62:63] op_sel_hi:[1,0,1]
	v_pk_mul_f32 v[62:63], v[68:69], v[74:75] op_sel_hi:[1,0] neg_lo:[0,1] neg_hi:[0,1]
	v_pk_mul_f32 v[170:171], v[68:69], v[76:77] op_sel_hi:[1,0] neg_lo:[0,1] neg_hi:[0,1]
	v_pk_fma_f32 v[62:63], v[64:65], v[100:101], v[62:63]
	v_pk_fma_f32 v[170:171], v[64:65], v[102:103], v[170:171]
	v_pk_fma_f32 v[92:93], v[72:73], v[96:97], v[62:63] op_sel_hi:[1,0,1]
	v_pk_fma_f32 v[100:101], v[72:73], v[78:79], v[170:171] op_sel_hi:[1,0,1]
	v_pk_mul_f32 v[62:63], v[54:55], v[74:75] op_sel_hi:[1,0] neg_lo:[0,1] neg_hi:[0,1]
	v_pk_mul_f32 v[54:55], v[54:55], v[76:77] op_sel_hi:[1,0] neg_lo:[0,1] neg_hi:[0,1]
	v_pk_fma_f32 v[62:63], v[50:51], v[104:105], v[62:63]
	v_pk_fma_f32 v[50:51], v[50:51], v[108:109], v[54:55]
	v_pk_fma_f32 v[94:95], v[58:59], v[96:97], v[62:63] op_sel_hi:[1,0,1]
	v_pk_fma_f32 v[102:103], v[58:59], v[78:79], v[50:51] op_sel_hi:[1,0,1]
	v_pk_mul_f32 v[50:51], v[56:57], v[74:75] op_sel_hi:[1,0] neg_lo:[0,1] neg_hi:[0,1]
	v_pk_mul_f32 v[170:171], v[56:57], v[76:77] op_sel_hi:[1,0] neg_lo:[0,1] neg_hi:[0,1]
	v_pk_fma_f32 v[50:51], v[52:53], v[110:111], v[50:51]
	v_pk_fma_f32 v[170:171], v[52:53], v[112:113], v[170:171]
	v_pk_fma_f32 v[96:97], v[60:61], v[96:97], v[50:51] op_sel_hi:[1,0,1]
	v_pk_fma_f32 v[104:105], v[60:61], v[78:79], v[170:171] op_sel_hi:[1,0,1]
	v_pk_mul_f32 v[50:51], v[48:49], v[92:93]
	v_pk_mul_f32 v[48:49], v[48:49], v[100:101]
	v_pk_fma_f32 v[50:51], v[46:47], v[90:91], v[50:51]
	v_pk_fma_f32 v[46:47], v[46:47], v[98:99], v[48:49]
	v_pk_fma_f32 v[48:49], v[44:45], v[96:97], v[50:51]
	v_pk_fma_f32 v[44:45], v[44:45], v[104:105], v[46:47]
	v_pk_fma_f32 v[48:49], v[42:43], v[94:95], v[48:49]
	v_pk_fma_f32 v[42:43], v[42:43], v[102:103], v[44:45]
	v_add_f32_e32 v163, v48, v49
	v_add_f32_e32 v164, v42, v43
	v_cndmask_b32_e64 v166, v159, v157, s[98:99]
	v_cndmask_b32_e64 v168, v163, v161, s[98:99]
	v_cndmask_b32_e64 v172, v160, v158, s[98:99]
	v_cndmask_b32_e64 v240, v164, v162, s[98:99]
	v_cndmask_b32_e64 v165, v157, v159, s[98:99]
	v_cndmask_b32_e64 v167, v161, v163, s[98:99]
	v_cndmask_b32_e64 v169, v158, v160, s[98:99]
	v_cndmask_b32_e64 v187, v162, v164, s[98:99]
	v_add_f32_dpp v165, v166, v165 quad_perm:[1,0,3,2] row_mask:0xf bank_mask:0xf bound_ctrl:1
	v_add_f32_dpp v167, v168, v167 quad_perm:[1,0,3,2] row_mask:0xf bank_mask:0xf bound_ctrl:1
	v_add_f32_dpp v169, v172, v169 quad_perm:[1,0,3,2] row_mask:0xf bank_mask:0xf bound_ctrl:1
	v_add_f32_dpp v187, v240, v187 quad_perm:[1,0,3,2] row_mask:0xf bank_mask:0xf bound_ctrl:1
	v_cndmask_b32_e64 v166, v167, v165, s[100:101]
	v_cndmask_b32_e64 v172, v187, v169, s[100:101]
	v_cndmask_b32_e64 v165, v165, v167, s[100:101]
	v_cndmask_b32_e64 v169, v169, v187, s[100:101]
	v_add_f32_dpp v165, v166, v165 quad_perm:[2,3,0,1] row_mask:0xf bank_mask:0xf bound_ctrl:1
	v_add_f32_dpp v169, v172, v169 quad_perm:[2,3,0,1] row_mask:0xf bank_mask:0xf bound_ctrl:1
	s_nop 0
	v_add_f32_dpp v165, v165, v165 row_shr:4 row_mask:0xf bank_mask:0xf bound_ctrl:1
	v_add_f32_dpp v169, v169, v169 row_shr:4 row_mask:0xf bank_mask:0xf bound_ctrl:1
	s_mov_b64 s[72:73], exec
	s_mov_b32 exec_lo, 0xf0f0f0f0
	s_mov_b32 exec_hi, 0xf0f0f0f0
	ds_write_b32 v253, v165
	ds_write_b32 v253, v169 offset:128
	s_mov_b64 exec, s[72:73]
	s_add_i32 s52, s52, 4
	v_add_u32_e32 v253, 0x400, v253
	v_add_u32_e32 v235, 0x400, v235
	s_cmp_gt_u32 s52, 29
	v_add_u32_e32 v252, 0x400, v252
	s_cbranch_scc0 .LBB0_2517
	s_branch .LBB0_2489
